# weight-conversion tiles (w_in, both copies), B2 bias prologue and sb-attention tail: per-element load->wait round trips replaced by batched loads
# speedup vs baseline: 1.0867x; 1.0207x over previous
; DI unsigned pk2(float lo, float hi) { f32x2 v = {lo, hi}; bf16x2_t b = __builtin_convertvector(v, bf16x2_t); return __builtin_bit_cast(unsigned, b); }
; DI void tr_tile(const float* __restrict__ src, int ld, int K, int k0, int n0, bool use_map, const float* __restrict__ scale, bf16_t* __restrict__ dst, int ldd, float* tile) {
;     ...
;   __syncthreads();
;   {
;     const int nl = tid >> 3, ks = tid & 7;
;     unsigned o[4];
; #pragma unroll
;     for (int e = 0; e < 4; ++e) o[e] = pk2(tile[(ks * 8 + 2 * e) * 65 + nl], tile[(ks * 8 + 2 * e + 1) * 65 + nl]);
;     *(u32x4*)(dst + (long)(n0 + nl) * ldd + k0 + ks * 8) = (u32x4){o[0], o[1], o[2], o[3]};
;   }
;   __syncthreads();
.Lmy_cvtp_tail:
	v_ashrrev_i32_e32 v3, 3, v1
	v_lshlrev_b32_e32 v1, 3, v1
	v_and_b32_e32 v1, 56, v1
	v_mul_u32_u24_e32 v6, 0x41, v1
	v_lshlrev_b32_e32 v4, 2, v3
	v_lshlrev_b32_e32 v8, 2, v6
	v_add3_u32 v10, 32, v4, v8
	v_add3_u32 v4, 32, v8, v4
	s_waitcnt lgkmcnt(0)
	s_barrier
	ds_read2_b32 v[6:7], v10 offset1:130
	ds_read2_b32 v[8:9], v4 offset0:65 offset1:195
	v_add_u32_e32 v10, 0x400, v10
	v_add_u32_e32 v4, 0x400, v4
	ds_read2_b32 v[10:11], v10 offset0:4 offset1:134
	ds_read2_b32 v[12:13], v4 offset0:69 offset1:199
	s_sub_i32 s0, s27, s14
	s_waitcnt lgkmcnt(2)
	v_cvt_pk_bf16_f32 v6, v6, v8
	v_cvt_pk_bf16_f32 v7, v7, v9
	v_add_u32_e32 v3, s58, v3
	s_waitcnt lgkmcnt(0)
	v_cvt_pk_bf16_f32 v8, v10, v12
	v_cvt_pk_bf16_f32 v9, v11, v13
	v_mov_b64_e32 v[10:11], s[10:11]
	v_mad_i64_i32 v[10:11], s[6:7], v3, s56, v[10:11]
	s_ashr_i32 s1, s0, 31
	v_lshl_add_u64 v[10:11], s[0:1], 1, v[10:11]
	v_lshlrev_b32_e32 v4, 1, v1
	s_add_i32 s57, s57, s94
	s_add_i32 s27, s27, s28
	v_lshl_add_u64 v[10:11], v[10:11], 0, v[4:5]
	s_cmpk_lt_i32 s57, 0x600
	global_store_dwordx4 v[10:11], v[6:9], off
	s_barrier
	s_cbranch_scc0 .LBB0_85

; DI int my_tid() { int t = threadIdx.x; asm volatile("" : "+v"(t)); return t; }
; DI void tr_tile(const float* __restrict__ src, int ld, int K, int k0, int n0, bool use_map, const float* __restrict__ scale, bf16_t* __restrict__ dst, int ldd, float* tile) {
;   const int tid = my_tid();
;   {
;     const int nl = tid & 63, kk = tid >> 6;
;     int n = n0 + nl; asm volatile("" : "+v"(n));
;     const int sc = use_map ? inmap(n) : n;
; #pragma unroll
;     for (int r = 0; r < 8; ++r) {
;       const int k = k0 + r * 8 + kk;
;       float v = 0.f;
;       if (sc >= 0) { v = src[(long)k * ld + sc]; if (scale) v *= scale[k]; }
;       tile[(r * 8 + kk) * 65 + nl] = v;
;     }
;   }
.LBB0_57:
	s_or_b64 exec, exec, s[0:1]
	v_ashrrev_i32_e32 v6, 6, v1
	v_cmp_gt_i32_e64 s[6:7], 0, v4
	v_lshl_add_u32 v3, v3, 2, 32
	v_mul_lo_u32 v12, v6, s54
	s_lshl_b32 s14, s59, 10
	v_readlane_b32 s70, v253, 14
	v_readlane_b32 s71, v253, 15
	v_readlane_b32 s68, v253, 12
	v_readlane_b32 s69, v253, 13
	v_subrev_u32_e32 v6, s14, v6
	v_add_u32_e32 v6, s27, v6
	v_ashrrev_i32_e32 v7, 31, v6
	v_lshl_add_u64 v[8:9], v[4:5], 2, s[70:71]
	v_add_u32_e32 v3, v3, v12
	v_mov_b32_e32 v56, 0
	v_mov_b32_e32 v64, 0
	v_mov_b32_e32 v57, 0
	v_mov_b32_e32 v65, 0
	v_mov_b32_e32 v58, 0
	v_mov_b32_e32 v66, 0
	v_mov_b32_e32 v59, 0
	v_mov_b32_e32 v67, 0
	v_mov_b32_e32 v60, 0
	v_mov_b32_e32 v68, 0
	v_mov_b32_e32 v61, 0
	v_mov_b32_e32 v69, 0
	v_mov_b32_e32 v62, 0
	v_mov_b32_e32 v70, 0
	v_mov_b32_e32 v63, 0
	v_mov_b32_e32 v71, 0
	s_mov_b64 s[60:61], exec
	s_andn2_b64 exec, exec, s[6:7]
	v_mad_i64_i32 v[72:73], s[16:17], v6, s55, v[8:9]
	global_load_dword v56, v[72:73], off
	v_add_u32_e32 v13, 8, v6
	v_mad_i64_i32 v[74:75], s[16:17], v13, s55, v[8:9]
	global_load_dword v57, v[74:75], off
	v_add_u32_e32 v13, 16, v6
	v_mad_i64_i32 v[76:77], s[16:17], v13, s55, v[8:9]
	global_load_dword v58, v[76:77], off
	v_add_u32_e32 v13, 24, v6
	v_mad_i64_i32 v[78:79], s[16:17], v13, s55, v[8:9]
	global_load_dword v59, v[78:79], off
	v_add_u32_e32 v13, 32, v6
	v_mad_i64_i32 v[80:81], s[16:17], v13, s55, v[8:9]
	global_load_dword v60, v[80:81], off
	v_add_u32_e32 v13, 40, v6
	v_mad_i64_i32 v[82:83], s[16:17], v13, s55, v[8:9]
	global_load_dword v61, v[82:83], off
	v_add_u32_e32 v13, 48, v6
	v_mad_i64_i32 v[84:85], s[16:17], v13, s55, v[8:9]
	global_load_dword v62, v[84:85], off
	v_add_u32_e32 v13, 56, v6
	v_mad_i64_i32 v[86:87], s[16:17], v13, s55, v[8:9]
	global_load_dword v63, v[86:87], off
	s_cmp_lg_u64 s[4:5], 0
	s_cbranch_scc1 .Lmy_cvtp_noscale
	v_lshl_add_u64 v[10:11], v[6:7], 2, s[68:69]
	global_load_dword v64, v[10:11], off
	global_load_dword v65, v[10:11], off offset:32
	global_load_dword v66, v[10:11], off offset:64
	global_load_dword v67, v[10:11], off offset:96
	global_load_dword v68, v[10:11], off offset:128
	global_load_dword v69, v[10:11], off offset:160
	global_load_dword v70, v[10:11], off offset:192
	global_load_dword v71, v[10:11], off offset:224
	s_mov_b64 exec, s[60:61]
	s_waitcnt vmcnt(0)
	v_mul_f32_e32 v56, v56, v64
	v_mul_f32_e32 v57, v57, v65
	v_mul_f32_e32 v58, v58, v66
	v_mul_f32_e32 v59, v59, v67
	v_mul_f32_e32 v60, v60, v68
	v_mul_f32_e32 v61, v61, v69
	v_mul_f32_e32 v62, v62, v70
	v_mul_f32_e32 v63, v63, v71
	s_branch .Lmy_cvtp_write
.Lmy_cvtp_noscale:
	s_mov_b64 exec, s[60:61]
	s_waitcnt vmcnt(0)
.Lmy_cvtp_write:
	ds_write_b32 v3, v56
	ds_write_b32 v3, v57 offset:2080
	ds_write_b32 v3, v58 offset:4160
	ds_write_b32 v3, v59 offset:6240
	ds_write_b32 v3, v60 offset:8320
	ds_write_b32 v3, v61 offset:10400
	ds_write_b32 v3, v62 offset:12480
	ds_write_b32 v3, v63 offset:14560
	s_branch .Lmy_cvtp_tail

; DI unsigned pk2(float lo, float hi) { f32x2 v = {lo, hi}; bf16x2_t b = __builtin_convertvector(v, bf16x2_t); return __builtin_bit_cast(unsigned, b); }
; DI float bflo(unsigned u) { return __uint_as_float(u << 16); }
; DI float bfhi(unsigned u) { return __uint_as_float(u & 0xffff0000u); }
; DI void sb_attn_wave(const Params& p, int b, int h, int t0, bf16_t* ybase) {
;     ...
;   for (int half = 0; half < 2; ++half) {
;     const long zo = ((long)b * SEQ + (half ? tB : tA)) * 512 + h * 64 + quad * 4;
;     const bf16_t* zp = p.sbz() + zo; bf16_t* yp = ybase + zo;
; #pragma unroll
;     for (int dt = 0; dt < 4; ++dt) {
;       const f32x4 o = half ? ob[dt] : oa[dt];
;       const u32x2 zz = *(const u32x2*)(zp + dt * 16);
;       *(u32x2*)(yp + dt * 16) = (u32x2){pk2(o[0] * bflo(zz[0]), o[1] * bfhi(zz[0])), pk2(o[2] * bflo(zz[1]), o[3] * bfhi(zz[1]))};
;     }
;   }
.LBB0_570:
	s_or_b64 exec, exec, s[4:5]
	s_add_u32 s4, s18, 0xc170000
	s_addc_u32 s5, s19, 0
	s_lshl_b32 s8, s17, 8
	s_and_b32 s36, s8, 0x7800
	v_lshl_add_u64 v[2:3], v[156:157], 0, s[36:37]
	s_lshl_b32 s8, s17, 7
	v_lshlrev_b64 v[2:3], 10, v[2:3]
	s_and_b32 s8, s8, 0x380
	v_lshl_add_u64 v[2:3], s[4:5], 0, v[2:3]
	v_lshl_or_b32 v0, v164, 3, s8
	v_lshl_add_u64 v[2:3], v[2:3], 0, v[0:1]
	v_lshl_add_u64 v[176:177], v[152:153], 0, s[36:37]
	v_lshlrev_b64 v[176:177], 10, v[176:177]
	v_lshl_add_u64 v[176:177], s[4:5], 0, v[176:177]
	v_lshl_add_u64 v[176:177], v[176:177], 0, v[0:1]
	global_load_dwordx2 v[178:179], v[2:3], off
	global_load_dwordx2 v[180:181], v[2:3], off offset:32
	global_load_dwordx2 v[182:183], v[2:3], off offset:64
	global_load_dwordx2 v[184:185], v[2:3], off offset:96
	global_load_dwordx2 v[190:191], v[176:177], off
	global_load_dwordx2 v[192:193], v[176:177], off offset:32
	global_load_dwordx2 v[194:195], v[176:177], off offset:64
	global_load_dwordx2 v[196:197], v[176:177], off offset:96
	s_mov_b64 s[4:5], 0
	s_waitcnt vmcnt(7)
	v_lshlrev_b32_e32 v216, 16, v178
	v_and_b32_e32 v217, 0xffff0000, v178
	v_lshlrev_b32_e32 v218, 16, v179
	v_and_b32_e32 v219, 0xffff0000, v179
	v_pk_mul_f32 v[216:217], v[48:49], v[216:217]
	v_pk_mul_f32 v[218:219], v[50:51], v[218:219]
	v_cvt_pk_bf16_f32 v198, v216, v217
	v_cvt_pk_bf16_f32 v199, v218, v219
	global_store_dwordx2 v[2:3], v[198:199], off
	s_waitcnt vmcnt(7)
	v_lshlrev_b32_e32 v216, 16, v180
	v_and_b32_e32 v217, 0xffff0000, v180
	v_lshlrev_b32_e32 v218, 16, v181
	v_and_b32_e32 v219, 0xffff0000, v181
	v_pk_mul_f32 v[216:217], v[44:45], v[216:217]
	v_pk_mul_f32 v[218:219], v[46:47], v[218:219]
	v_cvt_pk_bf16_f32 v200, v216, v217
	v_cvt_pk_bf16_f32 v201, v218, v219
	global_store_dwordx2 v[2:3], v[200:201], off offset:32
	s_waitcnt vmcnt(7)
	v_lshlrev_b32_e32 v216, 16, v182
	v_and_b32_e32 v217, 0xffff0000, v182
	v_lshlrev_b32_e32 v218, 16, v183
	v_and_b32_e32 v219, 0xffff0000, v183
	v_pk_mul_f32 v[216:217], v[24:25], v[216:217]
	v_pk_mul_f32 v[218:219], v[26:27], v[218:219]
	v_cvt_pk_bf16_f32 v206, v216, v217
	v_cvt_pk_bf16_f32 v207, v218, v219
	global_store_dwordx2 v[2:3], v[206:207], off offset:64
	s_waitcnt vmcnt(7)
	v_lshlrev_b32_e32 v216, 16, v184
	v_and_b32_e32 v217, 0xffff0000, v184
	v_lshlrev_b32_e32 v218, 16, v185
	v_and_b32_e32 v219, 0xffff0000, v185
	v_pk_mul_f32 v[216:217], v[20:21], v[216:217]
	v_pk_mul_f32 v[218:219], v[22:23], v[218:219]
	v_cvt_pk_bf16_f32 v198, v216, v217
	v_cvt_pk_bf16_f32 v199, v218, v219
	global_store_dwordx2 v[2:3], v[198:199], off offset:96
	s_waitcnt vmcnt(7)
	v_lshlrev_b32_e32 v216, 16, v190
	v_and_b32_e32 v217, 0xffff0000, v190
	v_lshlrev_b32_e32 v218, 16, v191
	v_and_b32_e32 v219, 0xffff0000, v191
	v_pk_mul_f32 v[216:217], v[16:17], v[216:217]
	v_pk_mul_f32 v[218:219], v[18:19], v[218:219]
	v_cvt_pk_bf16_f32 v200, v216, v217
	v_cvt_pk_bf16_f32 v201, v218, v219
	global_store_dwordx2 v[176:177], v[200:201], off
	s_waitcnt vmcnt(7)
	v_lshlrev_b32_e32 v216, 16, v192
	v_and_b32_e32 v217, 0xffff0000, v192
	v_lshlrev_b32_e32 v218, 16, v193
	v_and_b32_e32 v219, 0xffff0000, v193
	v_pk_mul_f32 v[216:217], v[12:13], v[216:217]
	v_pk_mul_f32 v[218:219], v[14:15], v[218:219]
	v_cvt_pk_bf16_f32 v206, v216, v217
	v_cvt_pk_bf16_f32 v207, v218, v219
	global_store_dwordx2 v[176:177], v[206:207], off offset:32
	s_waitcnt vmcnt(7)
	v_lshlrev_b32_e32 v216, 16, v194
	v_and_b32_e32 v217, 0xffff0000, v194
	v_lshlrev_b32_e32 v218, 16, v195
	v_and_b32_e32 v219, 0xffff0000, v195
	v_pk_mul_f32 v[216:217], v[8:9], v[216:217]
	v_pk_mul_f32 v[218:219], v[10:11], v[218:219]
	v_cvt_pk_bf16_f32 v198, v216, v217
	v_cvt_pk_bf16_f32 v199, v218, v219
	global_store_dwordx2 v[176:177], v[198:199], off offset:64
	s_waitcnt vmcnt(7)
	v_lshlrev_b32_e32 v216, 16, v196
	v_and_b32_e32 v217, 0xffff0000, v196
	v_lshlrev_b32_e32 v218, 16, v197
	v_and_b32_e32 v219, 0xffff0000, v197
	v_pk_mul_f32 v[216:217], v[4:5], v[216:217]
	v_pk_mul_f32 v[218:219], v[6:7], v[218:219]
	v_cvt_pk_bf16_f32 v200, v216, v217
	v_cvt_pk_bf16_f32 v201, v218, v219
	global_store_dwordx2 v[176:177], v[200:201], off offset:96

; DI void phaseB2(const Params& p0, int layer, unsigned char* lds) {
;     ...
;   float* bias_s = (float*)lds;
;   {
;     const float* b1 = p.b1eff() + (long)(layer * 2 + (tid >> 8)) * 16 * 256 + (tid & 255);
;     float sacc = 0.f;
; #pragma unroll
;     for (int kq = 0; kq < 16; ++kq) sacc += b1[kq * 256];
;     bias_s[tid] = sacc;
;   }
.LBB0_624:
	s_or_b64 exec, exec, s[4:5]
	s_mov_b64 s[4:5], 0
	s_waitcnt lgkmcnt(0)
	v_mov_b32_e32 v2, v210
	s_barrier
	v_readlane_b32 s1, v255, 14
	v_ashrrev_i32_e32 v0, 8, v2
	s_add_u32 s8, s92, s4
	v_lshl_add_u32 v4, s1, 1, v0
	v_ashrrev_i32_e32 v5, 31, v4
	s_addc_u32 s9, s93, s5
	v_lshlrev_b64 v[4:5], 14, v[4:5]
	v_mov_b32_e32 v0, 2
	v_lshl_add_u64 v[4:5], s[8:9], 0, v[4:5]
	v_lshlrev_b32_sdwa v0, v0, v2 dst_sel:DWORD dst_unused:UNUSED_PAD src0_sel:DWORD src1_sel:BYTE_0
	v_lshl_add_u64 v[4:5], v[4:5], 0, v[0:1]
	s_mov_b64 s[10:11], 0x12d0000
	v_lshl_add_u64 v[6:7], v[4:5], 0, s[10:11]
	s_mov_b64 s[10:11], 0x1000
	v_lshl_add_u64 v[8:9], v[6:7], 0, s[10:11]
	v_lshl_add_u64 v[56:57], v[8:9], 0, s[10:11]
	v_lshl_add_u64 v[58:59], v[56:57], 0, s[10:11]
	global_load_dword v60, v[6:7], off
	global_load_dword v61, v[6:7], off offset:1024
	global_load_dword v62, v[6:7], off offset:2048
	global_load_dword v63, v[6:7], off offset:3072
	global_load_dword v64, v[8:9], off
	global_load_dword v65, v[8:9], off offset:1024
	global_load_dword v66, v[8:9], off offset:2048
	global_load_dword v67, v[8:9], off offset:3072
	global_load_dword v68, v[56:57], off
	global_load_dword v69, v[56:57], off offset:1024
	global_load_dword v70, v[56:57], off offset:2048
	global_load_dword v71, v[56:57], off offset:3072
	global_load_dword v72, v[58:59], off
	global_load_dword v73, v[58:59], off offset:1024
	global_load_dword v74, v[58:59], off offset:2048
	global_load_dword v75, v[58:59], off offset:3072
	v_ashrrev_i32_e32 v3, 6, v2
	s_waitcnt vmcnt(15)
	v_add_f32_e32 v0, 0, v60
	s_waitcnt vmcnt(14)
	v_add_f32_e32 v0, v0, v61
	s_waitcnt vmcnt(13)
	v_add_f32_e32 v0, v0, v62
	s_waitcnt vmcnt(12)
	v_add_f32_e32 v0, v0, v63
	s_waitcnt vmcnt(11)
	v_add_f32_e32 v0, v0, v64
	s_waitcnt vmcnt(10)
	v_add_f32_e32 v0, v0, v65
	s_waitcnt vmcnt(9)
	v_add_f32_e32 v0, v0, v66
	s_waitcnt vmcnt(8)
	v_add_f32_e32 v0, v0, v67
	s_waitcnt vmcnt(7)
	v_add_f32_e32 v0, v0, v68
	s_waitcnt vmcnt(6)
	v_add_f32_e32 v0, v0, v69
	s_waitcnt vmcnt(5)
	v_add_f32_e32 v0, v0, v70
	s_waitcnt vmcnt(4)
	v_add_f32_e32 v0, v0, v71
	s_waitcnt vmcnt(3)
	v_add_f32_e32 v0, v0, v72
	s_waitcnt vmcnt(2)
	v_add_f32_e32 v0, v0, v73
	s_waitcnt vmcnt(1)
	v_add_f32_e32 v0, v0, v74
	s_waitcnt vmcnt(0)
	v_add_f32_e32 v0, v0, v75
	v_cmp_gt_i32_e32 vcc, 2, v3
	v_lshl_add_u32 v4, v2, 2, 32
	ds_write_b32 v4, v0
	s_waitcnt lgkmcnt(0)
	s_barrier
	s_and_saveexec_b64 s[10:11], vcc
	s_cbranch_execz .LBB0_650
	v_readlane_b32 s1, v254, 44
	s_nop 1
	v_add_u32_e32 v29, s1, v3
	s_movk_i32 s1, 0x200
	v_cmp_gt_i32_e32 vcc, s1, v29
	s_and_b64 exec, exec, vcc
	s_cbranch_execz .LBB0_650
	s_add_u32 s12, s8, 0x1f5f0000
	s_mov_b32 s1, s37
	s_addc_u32 s13, s9, 0
	s_lshl_b64 s[0:1], s[0:1], 2
	v_bfe_u32 v0, v2, 4, 2
	s_add_u32 s0, s8, s0
	v_and_b32_e32 v44, 15, v2
	v_lshrrev_b32_e32 v6, 6, v2
	v_lshlrev_b32_e32 v2, 5, v0
	v_lshlrev_b32_e32 v28, 2, v0
	s_addc_u32 s1, s9, s1
	v_lshlrev_b32_e32 v0, 4, v0
	v_lshl_add_u64 v[4:5], s[0:1], 0, v[0:1]
	s_mov_b64 s[0:1], 0x1f670400
	v_lshl_add_u64 v[30:31], v[4:5], 0, s[0:1]
	s_add_u32 s0, s8, 0x1af0000
	s_addc_u32 s1, s9, 0
	s_add_u32 s14, s8, 0x1b30000
	s_addc_u32 s15, s9, 0
	s_add_u32 s16, s8, 0x1f570000
	v_mov_b32_e32 v3, v1
	v_readlane_b32 s8, v254, 44
	v_lshl_or_b32 v0, v44, 9, v0
	v_lshlrev_b32_e32 v26, 8, v44
	v_add_u32_e32 v45, 32, v2
	s_addc_u32 s17, s9, 0
	v_mov_b32_e32 v27, v1
	v_lshl_add_u64 v[32:33], s[92:93], 0, v[2:3]
	v_add_u16_e32 v46, s8, v6
	v_lshl_add_u64 v[34:35], s[92:93], 0, v[0:1]
	s_mov_b64 s[18:19], 0
	s_branch .LBB0_628

; DI unsigned pk2(float lo, float hi) { f32x2 v = {lo, hi}; bf16x2_t b = __builtin_convertvector(v, bf16x2_t); return __builtin_bit_cast(unsigned, b); }
; DI void tr_tile(const float* __restrict__ src, int ld, int K, int k0, int n0, bool use_map, const float* __restrict__ scale, bf16_t* __restrict__ dst, int ldd, float* tile) {
;     ...
;   __syncthreads();
;   {
;     const int nl = tid >> 3, ks = tid & 7;
;     unsigned o[4];
; #pragma unroll
;     for (int e = 0; e < 4; ++e) o[e] = pk2(tile[(ks * 8 + 2 * e) * 65 + nl], tile[(ks * 8 + 2 * e + 1) * 65 + nl]);
;     *(u32x4*)(dst + (long)(n0 + nl) * ldd + k0 + ks * 8) = (u32x4){o[0], o[1], o[2], o[3]};
;   }
;   __syncthreads();
.Lmy_cvt_tail:
	v_ashrrev_i32_e32 v0, 3, v8
	v_and_b32_e32 v8, 56, v2
	v_mul_u32_u24_e32 v2, 0x41, v8
	v_lshlrev_b32_e32 v4, 2, v0
	v_lshlrev_b32_e32 v5, 2, v2
	v_add3_u32 v6, 32, v4, v5
	v_add3_u32 v7, 32, v5, v4
	s_waitcnt lgkmcnt(0)
	s_barrier
	ds_read2_b32 v[2:3], v6 offset1:130
	ds_read2_b32 v[4:5], v7 offset0:65 offset1:195
	s_sub_i32 s8, s27, s18
	v_add_u32_e32 v0, s29, v0
	s_movk_i32 s9, 0x880
	s_add_i32 s28, s28, s94
	s_waitcnt lgkmcnt(0)
	v_cvt_pk_bf16_f32 v2, v2, v4
	v_add_u32_e32 v4, 0x400, v6
	v_add_u32_e32 v6, 0x400, v7
	v_cvt_pk_bf16_f32 v3, v3, v5
	ds_read2_b32 v[4:5], v4 offset0:4 offset1:134
	ds_read2_b32 v[6:7], v6 offset0:69 offset1:199
	s_add_i32 s27, s27, s26
	s_waitcnt lgkmcnt(0)
	v_cvt_pk_bf16_f32 v4, v4, v6
	v_cvt_pk_bf16_f32 v5, v5, v7
	v_mov_b64_e32 v[6:7], s[4:5]
	v_mad_i64_i32 v[6:7], s[10:11], v0, s9, v[6:7]
	s_ashr_i32 s9, s8, 31
	v_lshl_add_u64 v[6:7], s[8:9], 1, v[6:7]
	v_lshlrev_b32_e32 v0, 1, v8
	v_lshl_add_u64 v[6:7], v[6:7], 0, v[0:1]
	s_cmpk_lt_i32 s28, 0x600
	global_store_dwordx4 v[6:7], v[2:5], off
	s_barrier
	s_cbranch_scc0 .LBB0_1080

; DI int my_tid() { int t = threadIdx.x; asm volatile("" : "+v"(t)); return t; }
; DI void tr_tile(const float* __restrict__ src, int ld, int K, int k0, int n0, bool use_map, const float* __restrict__ scale, bf16_t* __restrict__ dst, int ldd, float* tile) {
;   const int tid = my_tid();
;   {
;     const int nl = tid & 63, kk = tid >> 6;
;     int n = n0 + nl; asm volatile("" : "+v"(n));
;     const int sc = use_map ? inmap(n) : n;
; #pragma unroll
;     for (int r = 0; r < 8; ++r) {
;       const int k = k0 + r * 8 + kk;
;       float v = 0.f;
;       if (sc >= 0) { v = src[(long)k * ld + sc]; if (scale) v *= scale[k]; }
;       tile[(r * 8 + kk) * 65 + nl] = v;
;     }
;   }
.LBB0_1052:
	s_or_b64 exec, exec, s[8:9]
	v_ashrrev_i32_e32 v3, 6, v8
	s_movk_i32 s8, 0x104
	v_cmp_gt_i32_e64 s[10:11], 0, v0
	v_lshl_add_u32 v9, v2, 2, 32
	v_mul_lo_u32 v10, v3, s8
	s_lshl_b32 s18, s30, 10
	v_readlane_b32 s8, v254, 48
	v_readlane_b32 s9, v254, 49
	v_subrev_u32_e32 v2, s18, v3
	v_add_u32_e32 v2, s27, v2
	v_ashrrev_i32_e32 v3, 31, v2
	v_lshl_add_u64 v[4:5], v[0:1], 2, s[12:13]
	v_add_u32_e32 v11, v9, v10
	v_mov_b32_e32 v56, 0
	v_mov_b32_e32 v64, 0
	v_mov_b32_e32 v57, 0
	v_mov_b32_e32 v65, 0
	v_mov_b32_e32 v58, 0
	v_mov_b32_e32 v66, 0
	v_mov_b32_e32 v59, 0
	v_mov_b32_e32 v67, 0
	v_mov_b32_e32 v60, 0
	v_mov_b32_e32 v68, 0
	v_mov_b32_e32 v61, 0
	v_mov_b32_e32 v69, 0
	v_mov_b32_e32 v62, 0
	v_mov_b32_e32 v70, 0
	v_mov_b32_e32 v63, 0
	v_mov_b32_e32 v71, 0
	s_movk_i32 s19, 0x5c60
	s_mov_b64 s[16:17], exec
	s_andn2_b64 exec, exec, s[10:11]
	v_mad_i64_i32 v[72:73], s[38:39], v2, s19, v[4:5]
	global_load_dword v56, v[72:73], off
	v_add_u32_e32 v12, 8, v2
	v_mad_i64_i32 v[74:75], s[38:39], v12, s19, v[4:5]
	global_load_dword v57, v[74:75], off
	v_add_u32_e32 v12, 16, v2
	v_mad_i64_i32 v[76:77], s[38:39], v12, s19, v[4:5]
	global_load_dword v58, v[76:77], off
	v_add_u32_e32 v12, 24, v2
	v_mad_i64_i32 v[78:79], s[38:39], v12, s19, v[4:5]
	global_load_dword v59, v[78:79], off
	v_add_u32_e32 v12, 32, v2
	v_mad_i64_i32 v[80:81], s[38:39], v12, s19, v[4:5]
	global_load_dword v60, v[80:81], off
	v_add_u32_e32 v12, 40, v2
	v_mad_i64_i32 v[82:83], s[38:39], v12, s19, v[4:5]
	global_load_dword v61, v[82:83], off
	v_add_u32_e32 v12, 48, v2
	v_mad_i64_i32 v[84:85], s[38:39], v12, s19, v[4:5]
	global_load_dword v62, v[84:85], off
	v_add_u32_e32 v12, 56, v2
	v_mad_i64_i32 v[86:87], s[38:39], v12, s19, v[4:5]
	global_load_dword v63, v[86:87], off
	s_cmp_lg_u64 s[8:9], 0
	s_cbranch_scc0 .Lmy_cvt_noscale
	v_lshl_add_u64 v[6:7], v[2:3], 2, s[14:15]
	global_load_dword v64, v[6:7], off
	global_load_dword v65, v[6:7], off offset:32
	global_load_dword v66, v[6:7], off offset:64
	global_load_dword v67, v[6:7], off offset:96
	global_load_dword v68, v[6:7], off offset:128
	global_load_dword v69, v[6:7], off offset:160
	global_load_dword v70, v[6:7], off offset:192
	global_load_dword v71, v[6:7], off offset:224
	s_mov_b64 exec, s[16:17]
	s_waitcnt vmcnt(0)
	v_mul_f32_e32 v56, v56, v64
	v_mul_f32_e32 v57, v57, v65
	v_mul_f32_e32 v58, v58, v66
	v_mul_f32_e32 v59, v59, v67
	v_mul_f32_e32 v60, v60, v68
	v_mul_f32_e32 v61, v61, v69
	v_mul_f32_e32 v62, v62, v70
	v_mul_f32_e32 v63, v63, v71
	s_branch .Lmy_cvt_write
.Lmy_cvt_noscale:
	s_mov_b64 exec, s[16:17]
	s_waitcnt vmcnt(0)
.Lmy_cvt_write:
	ds_write_b32 v11, v56
	ds_write_b32 v11, v57 offset:2080
	ds_write_b32 v11, v58 offset:4160
	ds_write_b32 v11, v59 offset:6240
	ds_write_b32 v11, v60 offset:8320
	ds_write_b32 v11, v61 offset:10400
	ds_write_b32 v11, v62 offset:12480
	ds_write_b32 v11, v63 offset:14560
	v_lshlrev_b32_e32 v2, 3, v8
	s_branch .Lmy_cvt_tail
